# ml_p1 staging: both V slices requested together (one round trip instead of two), on top of v82
# baseline (speedup 1.0000x reference)
; __device__ __forceinline__ float bflo(unsigned u) { return __uint_as_float(u << 16); }
; __device__ __forceinline__ float bfhi(unsigned u) { return __uint_as_float(u & 0xffff0000u); }
; __device__ __forceinline__ void ml_p1_item(const Params& p, int l, int item, char* ldsraw) {
;     ...
; #pragma unroll
;     for (int i = 0; i < 2; i++) {
;       const int ci = tid + 256 * i; const int row = ci >> 3, c8 = ci & 7;
;       const u32x4 w = *(const u32x4*)(P + (size_t)(tokb + row) * PIN + C_ML + 256 + h * 64 + c8 * 8);
;       *(f32x4*)(Vs + row * 64 + c8 * 8) = (f32x4){bflo(w[0]), bfhi(w[0]), bflo(w[1]), bfhi(w[1])};
;       *(f32x4*)(Vs + row * 64 + c8 * 8 + 4) = (f32x4){bflo(w[2]), bfhi(w[2]), bflo(w[3]), bfhi(w[3])};
;     }
;     __syncthreads();
;     const int t = tid >> 2, dq = tid & 3;
; #pragma unroll
;     for (int i = 0; i < 8; i++) { int d = dq * 8 + i; Ks[t * 33 + d] = ml_conv_lds(raw, wl, t, 32 + d); }
.LBB0_553:
	s_or_b64 exec, exec, s[26:27]
	v_ashrrev_i32_e32 v20, 3, v0
	v_add_u32_e32 v4, s3, v20
	v_mov_b64_e32 v[12:13], s[28:29]
	v_lshlrev_b32_e32 v1, 3, v0
	v_mad_i64_i32 v[4:5], s[26:27], v4, s69, v[12:13]
	v_and_b32_e32 v2, 56, v1
	s_lshl_b32 s26, s2, 7
	s_mov_b32 s27, s89
	v_lshl_add_u32 v14, v2, 2, 0
	v_lshl_add_u64 v[4:5], v[4:5], 0, s[26:27]
	v_lshlrev_b32_e32 v2, 1, v2
	v_lshl_add_u64 v[4:5], v[4:5], 0, v[2:3]
	global_load_dwordx4 v[4:7], v[4:5], off offset:3456
	v_add_u32_e32 v154, 0x100, v0
	v_ashrrev_i32_e32 v154, 3, v154
	v_add_u32_e32 v154, s3, v154
	v_mad_i64_i32 v[156:157], s[30:31], v154, s69, v[12:13]
	v_lshl_add_u64 v[156:157], v[156:157], 0, s[26:27]
	v_lshl_add_u64 v[156:157], v[156:157], 0, v[2:3]
	global_load_dwordx4 v[150:153], v[156:157], off offset:3456
	v_lshl_add_u32 v15, v20, 8, v14
	v_ashrrev_i32_e32 v22, 2, v0
	v_and_b32_e32 v1, 24, v1
	s_movk_i32 s4, 0x84
	v_cmp_gt_i32_e32 vcc, 64, v0
	s_waitcnt vmcnt(0)
	v_lshlrev_b32_e32 v8, 16, v4
	v_and_b32_e32 v9, 0xffff0000, v4
	v_lshlrev_b32_e32 v10, 16, v5
	v_and_b32_e32 v11, 0xffff0000, v5
	v_lshlrev_b32_e32 v4, 16, v6
	v_and_b32_e32 v5, 0xffff0000, v6
	v_lshlrev_b32_e32 v6, 16, v7
	v_and_b32_e32 v7, 0xffff0000, v7
	ds_write_b128 v15, v[4:7] offset:8464
	v_add_u32_e32 v4, 0x100, v0
	ds_write_b128 v15, v[8:11] offset:8448
	v_ashrrev_i32_e32 v15, 3, v4
	v_add_u32_e32 v4, s3, v15
	v_mad_i64_i32 v[4:5], s[30:31], v4, s69, v[12:13]
	v_lshl_add_u64 v[4:5], v[4:5], 0, s[26:27]
	v_lshl_add_u64 v[4:5], v[4:5], 0, v[2:3]
	v_mov_b32_e32 v4, v150
	v_mov_b32_e32 v5, v151
	v_mov_b32_e32 v6, v152
	v_mov_b32_e32 v7, v153
	v_lshl_add_u32 v2, v15, 8, v14
	s_waitcnt vmcnt(0)
	v_lshlrev_b32_e32 v8, 16, v4
	v_and_b32_e32 v9, 0xffff0000, v4
	v_lshlrev_b32_e32 v10, 16, v5
	v_and_b32_e32 v11, 0xffff0000, v5
	v_lshlrev_b32_e32 v4, 16, v6
	v_and_b32_e32 v5, 0xffff0000, v6
	v_lshlrev_b32_e32 v6, 16, v7
	v_and_b32_e32 v7, 0xffff0000, v7
	ds_write_b128 v2, v[8:11] offset:8448
	ds_write_b128 v2, v[4:7] offset:8464
	v_lshlrev_b32_e32 v4, 7, v22
	v_lshl_add_u32 v2, v1, 2, 0
	v_lshlrev_b32_e32 v1, 1, v1
	v_add3_u32 v1, 0, v4, v1
	s_waitcnt lgkmcnt(0)
	s_barrier
	ds_read_b128 v[4:7], v1 offset:25664
	ds_read_b128 v[12:15], v1 offset:25792
	ds_read_b32 v23, v2 offset:35328
	ds_read_b32 v9, v2 offset:34304
	ds_read_b128 v[16:19], v1 offset:25920
	s_waitcnt lgkmcnt(4)
	v_lshlrev_b32_e32 v8, 16, v4
	ds_read_b32 v24, v2 offset:35072
	v_and_b32_e32 v4, 0xffff0000, v4
	s_waitcnt lgkmcnt(2)
	v_fmac_f32_e32 v23, v9, v8
	ds_read_b32 v9, v2 offset:34560
	v_lshlrev_b32_e32 v8, 16, v12
	s_waitcnt lgkmcnt(0)
	v_fmac_f32_e32 v23, v9, v8
	ds_read_b32 v9, v2 offset:34816
	v_lshlrev_b32_e32 v8, 16, v16
	s_waitcnt lgkmcnt(0)
	v_fmac_f32_e32 v23, v9, v8
	ds_read_b128 v[8:11], v1 offset:26048
	s_waitcnt lgkmcnt(0)
	v_lshlrev_b32_e32 v1, 16, v8
	v_fmac_f32_e32 v23, v24, v1
	v_mul_f32_e32 v1, 0xbfb8aa3b, v23
	v_exp_f32_e32 v1, v1
	s_nop 0
	v_add_f32_e32 v1, 1.0, v1
	v_rcp_f32_e32 v1, v1
	s_nop 0
	v_mul_f32_e32 v1, v23, v1
	v_mad_u64_u32 v[22:23], s[26:27], v22, s4, v[2:3]
	ds_write_b32 v22, v1
	ds_read_b32 v1, v2 offset:35332
	ds_read_b32 v23, v2 offset:34308
	s_waitcnt lgkmcnt(0)
	v_fmac_f32_e32 v1, v23, v4
	v_and_b32_e32 v4, 0xffff0000, v12
	ds_read_b32 v12, v2 offset:34564
	s_waitcnt lgkmcnt(0)
	v_fmac_f32_e32 v1, v12, v4
	ds_read_b32 v12, v2 offset:34820
	v_and_b32_e32 v4, 0xffff0000, v16
	v_mov_b32_e32 v16, 0
	s_waitcnt lgkmcnt(0)
	v_fmac_f32_e32 v1, v12, v4
	v_and_b32_e32 v4, 0xffff0000, v8
	ds_read_b32 v8, v2 offset:35076
	s_waitcnt lgkmcnt(0)
	v_fmac_f32_e32 v1, v8, v4
	v_mul_f32_e32 v4, 0xbfb8aa3b, v1
	v_exp_f32_e32 v4, v4
	s_nop 0
	v_add_f32_e32 v4, 1.0, v4
	v_rcp_f32_e32 v4, v4
	s_nop 0
	v_mul_f32_e32 v1, v1, v4
	ds_write_b32 v22, v1 offset:4
	ds_read_b32 v1, v2 offset:35336
	ds_read_b32 v8, v2 offset:34312
	v_lshlrev_b32_e32 v4, 16, v5
	s_waitcnt lgkmcnt(0)
	v_fmac_f32_e32 v1, v8, v4
	ds_read_b32 v8, v2 offset:34568
	v_lshlrev_b32_e32 v4, 16, v13
	s_waitcnt lgkmcnt(0)
	v_fmac_f32_e32 v1, v8, v4
	ds_read_b32 v8, v2 offset:34824
	v_lshlrev_b32_e32 v4, 16, v17
	s_waitcnt lgkmcnt(0)
	v_fmac_f32_e32 v1, v8, v4
	ds_read_b32 v8, v2 offset:35080
	v_lshlrev_b32_e32 v4, 16, v9
	s_waitcnt lgkmcnt(0)
	v_fmac_f32_e32 v1, v8, v4
	v_mul_f32_e32 v4, 0xbfb8aa3b, v1
	v_exp_f32_e32 v4, v4
	s_nop 0
	v_add_f32_e32 v4, 1.0, v4
	v_rcp_f32_e32 v4, v4
	s_nop 0
	v_mul_f32_e32 v1, v1, v4
	ds_write_b32 v22, v1 offset:8
	ds_read_b32 v1, v2 offset:35340
	v_and_b32_e32 v4, 0xffff0000, v5
	ds_read_b32 v5, v2 offset:34316
	s_waitcnt lgkmcnt(0)
	v_fmac_f32_e32 v1, v5, v4
	ds_read_b32 v5, v2 offset:34572
	v_and_b32_e32 v4, 0xffff0000, v13
	s_waitcnt lgkmcnt(0)
	v_fmac_f32_e32 v1, v5, v4
	ds_read_b32 v5, v2 offset:34828
	v_and_b32_e32 v4, 0xffff0000, v17
	v_mov_b32_e32 v17, 0
	s_waitcnt lgkmcnt(0)
	v_fmac_f32_e32 v1, v5, v4
	ds_read_b32 v5, v2 offset:35084
	v_and_b32_e32 v4, 0xffff0000, v9
	s_waitcnt lgkmcnt(0)
	v_fmac_f32_e32 v1, v5, v4
	v_mul_f32_e32 v4, 0xbfb8aa3b, v1
	v_exp_f32_e32 v4, v4
	s_nop 0
	v_add_f32_e32 v4, 1.0, v4
	v_rcp_f32_e32 v4, v4
	s_nop 0
	v_mul_f32_e32 v1, v1, v4
	ds_write_b32 v22, v1 offset:12
	ds_read_b32 v1, v2 offset:35344
	ds_read_b32 v5, v2 offset:34320
	v_lshlrev_b32_e32 v4, 16, v6
	s_waitcnt lgkmcnt(0)
	v_fmac_f32_e32 v1, v5, v4
	ds_read_b32 v5, v2 offset:34576
	v_lshlrev_b32_e32 v4, 16, v14
	s_waitcnt lgkmcnt(0)
	v_fmac_f32_e32 v1, v5, v4
	ds_read_b32 v5, v2 offset:34832
	v_lshlrev_b32_e32 v4, 16, v18
	s_waitcnt lgkmcnt(0)
	v_fmac_f32_e32 v1, v5, v4
	ds_read_b32 v5, v2 offset:35088
	v_lshlrev_b32_e32 v4, 16, v10
	s_waitcnt lgkmcnt(0)
; __device__ __forceinline__ void ml_p1_item(const Params& p, int l, int item, char* ldsraw) {
;     ...
;     for (int i = 0; i < 8; i++) { int d = dq * 8 + i; Ks[t * 33 + d] = ml_conv_lds(raw, wl, t, 32 + d); }
;     ...
;   if (tid < 64) {
	v_fmac_f32_e32 v1, v5, v4
	v_mul_f32_e32 v4, 0xbfb8aa3b, v1
	v_exp_f32_e32 v4, v4
	s_nop 0
	v_add_f32_e32 v4, 1.0, v4
	v_rcp_f32_e32 v4, v4
	s_nop 0
	v_mul_f32_e32 v1, v1, v4
	ds_write_b32 v22, v1 offset:16
	ds_read_b32 v1, v2 offset:35348
	ds_read_b32 v5, v2 offset:34324
	v_and_b32_e32 v4, 0xffff0000, v6
	s_waitcnt lgkmcnt(0)
	v_fmac_f32_e32 v1, v5, v4
	ds_read_b32 v5, v2 offset:34580
	v_and_b32_e32 v4, 0xffff0000, v14
	s_waitcnt lgkmcnt(0)
	v_fmac_f32_e32 v1, v5, v4
	ds_read_b32 v5, v2 offset:34836
	v_and_b32_e32 v4, 0xffff0000, v18
	s_waitcnt lgkmcnt(0)
	v_fmac_f32_e32 v1, v5, v4
	ds_read_b32 v5, v2 offset:35092
	v_and_b32_e32 v4, 0xffff0000, v10
	s_waitcnt lgkmcnt(0)
	v_fmac_f32_e32 v1, v5, v4
	v_mul_f32_e32 v4, 0xbfb8aa3b, v1
	v_exp_f32_e32 v4, v4
	s_nop 0
	v_add_f32_e32 v4, 1.0, v4
	v_rcp_f32_e32 v4, v4
	s_nop 0
	v_mul_f32_e32 v1, v1, v4
	ds_write_b32 v22, v1 offset:20
	ds_read_b32 v1, v2 offset:35352
	ds_read_b32 v5, v2 offset:34328
	v_lshlrev_b32_e32 v4, 16, v7
	s_waitcnt lgkmcnt(0)
	v_fmac_f32_e32 v1, v5, v4
	ds_read_b32 v5, v2 offset:34584
	v_lshlrev_b32_e32 v4, 16, v15
	s_waitcnt lgkmcnt(0)
	v_fmac_f32_e32 v1, v5, v4
	ds_read_b32 v5, v2 offset:34840
	v_lshlrev_b32_e32 v4, 16, v19
	s_waitcnt lgkmcnt(0)
	v_fmac_f32_e32 v1, v5, v4
	ds_read_b32 v5, v2 offset:35096
	v_lshlrev_b32_e32 v4, 16, v11
	s_waitcnt lgkmcnt(0)
	v_fmac_f32_e32 v1, v5, v4
	v_mul_f32_e32 v4, 0xbfb8aa3b, v1
	v_exp_f32_e32 v4, v4
	s_nop 0
	v_add_f32_e32 v4, 1.0, v4
	v_rcp_f32_e32 v4, v4
	s_nop 0
	v_mul_f32_e32 v1, v1, v4
	ds_write_b32 v22, v1 offset:24
	ds_read_b32 v1, v2 offset:35356
	ds_read_b32 v5, v2 offset:34332
	v_and_b32_e32 v4, 0xffff0000, v7
	s_waitcnt lgkmcnt(0)
	v_fmac_f32_e32 v1, v5, v4
	ds_read_b32 v5, v2 offset:34588
	v_and_b32_e32 v4, 0xffff0000, v15
	s_waitcnt lgkmcnt(0)
	v_fmac_f32_e32 v1, v5, v4
	ds_read_b32 v5, v2 offset:34844
	ds_read_b32 v2, v2 offset:35100
	v_and_b32_e32 v4, 0xffff0000, v19
	s_waitcnt lgkmcnt(1)
	v_fmac_f32_e32 v1, v5, v4
	v_and_b32_e32 v4, 0xffff0000, v11
	s_waitcnt lgkmcnt(0)
	v_fmac_f32_e32 v1, v2, v4
	v_mul_f32_e32 v2, 0xbfb8aa3b, v1
	v_exp_f32_e32 v2, v2
	s_nop 0
	v_add_f32_e32 v2, 1.0, v2
	v_rcp_f32_e32 v2, v2
	s_nop 0
	v_mul_f32_e32 v1, v1, v2
	ds_write_b32 v22, v1 offset:28
	s_and_saveexec_b64 s[26:27], vcc
	s_cbranch_execz .LBB0_579
; __device__ __forceinline__ float bf2f(unsigned short b) { return __uint_as_float(((unsigned)b) << 16); }
; __device__ __forceinline__ void ml_p1_item(const Params& p, int l, int item, char* ldsraw) {
;     ...
;   if (tid < 64) {
;     const int t = tid;
;     const float ip = bf2f(P[(size_t)(tokb + t) * PIN + C_ML + 512 + h]) + p.i_bias[l * 4 + h];
;     const float fp = bf2f(P[(size_t)(tokb + t) * PIN + C_ML + 516 + h]) + p.f_bias[l * 4 + h];
;     const float lf = fminf(fp, 0.f) - log1pf(__expf(-fabsf(fp)));
;     volatile float* sc = G + 64;
;     const float g = wave_scan_add_lds(sc, t, lf);
;     glast = sc[63];
;     const float a = glast - g + ip;
;     amax = wave_scan_max_lds(sc + 64, t, a);
;     amax = sc[64 + 63];
;     G[t] = __expf(a - amax);
	v_add_u32_e32 v1, s3, v0
	v_mov_b64_e32 v[4:5], s[28:29]
	v_mad_i64_i32 v[4:5], s[28:29], v1, s69, v[4:5]
	v_readlane_b32 s3, v255, 14
	s_lshl_b32 s28, s2, 1
	s_or_b32 s2, s2, s3
	s_ashr_i32 s3, s2, 31
	v_readlane_b32 s4, v252, 19
	s_mov_b32 s29, s89
	s_lshl_b64 s[2:3], s[2:3], 2
	v_readlane_b32 s16, v252, 31
	v_lshl_add_u64 v[4:5], v[4:5], 0, s[28:29]
	v_readlane_b32 s17, v252, 32
	s_add_u32 s28, s16, s2
	v_readlane_b32 s18, v252, 33
	s_addc_u32 s29, s17, s3
	v_readlane_b32 s19, v252, 34
	s_add_u32 s2, s18, s2
	global_load_ushort v2, v[4:5], off offset:3968
	global_load_dword v6, v3, s[28:29]
	global_load_ushort v1, v[4:5], off offset:3976
	s_addc_u32 s3, s19, s3
	global_load_dword v4, v3, s[2:3]
	s_mov_b32 s2, 0xbfb8aa3b
	v_mov_b32_e32 v7, 0
	v_readlane_b32 s5, v252, 20
	v_readlane_b32 s6, v252, 21
	v_readlane_b32 s7, v252, 22
	v_readlane_b32 s8, v252, 23
	v_readlane_b32 s9, v252, 24
	v_readlane_b32 s10, v252, 25
	v_readlane_b32 s11, v252, 26
	v_readlane_b32 s12, v252, 27
	v_readlane_b32 s13, v252, 28
	v_readlane_b32 s14, v252, 29
	v_readlane_b32 s15, v252, 30
	s_waitcnt vmcnt(1)
	v_lshlrev_b32_e32 v1, 16, v1
	s_waitcnt vmcnt(0)
	v_add_f32_e32 v1, v4, v1
	v_min_f32_e32 v8, 0, v1
	v_mul_f32_e64 v1, |v1|, s2
	v_exp_f32_e32 v1, v1
	s_mov_b32 s2, 0x3f2aaaab
	v_add_f32_e32 v9, 1.0, v1
	v_add_f32_e32 v4, -1.0, v9
	v_sub_f32_e32 v5, v4, v9
	v_add_f32_e32 v5, 1.0, v5
	v_sub_f32_e32 v4, v1, v4
	v_add_f32_e32 v10, v4, v5
	v_frexp_mant_f32_e32 v4, v9
	v_cmp_gt_f32_e32 vcc, s2, v4
	v_cvt_f64_f32_e32 v[4:5], v9
	v_frexp_exp_i32_f64_e32 v4, v[4:5]
	v_subbrev_co_u32_e32 v4, vcc, 0, v4, vcc
	v_sub_u32_e32 v5, 0, v4
	v_ldexp_f32 v9, v9, v5
	v_ldexp_f32 v5, v10, v5
	v_add_f32_e32 v10, -1.0, v9
	v_add_f32_e32 v11, 1.0, v10
	v_sub_f32_e32 v11, v9, v11
	v_add_f32_e32 v11, v5, v11
	v_add_f32_e32 v12, v10, v11
	v_sub_f32_e32 v10, v12, v10
	v_sub_f32_e32 v10, v11, v10
	v_add_f32_e32 v11, 1.0, v9
	v_add_f32_e32 v13, -1.0, v11
	v_sub_f32_e32 v9, v9, v13
	v_add_f32_e32 v5, v5, v9
	v_add_f32_e32 v9, v11, v5
	v_sub_f32_e32 v11, v9, v11
	v_sub_f32_e32 v5, v5, v11
	v_rcp_f32_e32 v11, v9
	v_cvt_f32_i32_e32 v4, v4
	s_mov_b32 s2, 0x3f317218
	v_mul_f32_e32 v13, v12, v11
	v_mul_f32_e32 v14, v9, v13
	v_fma_f32 v15, v13, v9, -v14
	v_fmac_f32_e32 v15, v13, v5
	v_add_f32_e32 v16, v14, v15
	v_sub_f32_e32 v17, v12, v16
	v_sub_f32_e32 v12, v12, v17
	v_sub_f32_e32 v14, v16, v14
	v_sub_f32_e32 v12, v12, v16
	v_add_f32_e32 v10, v10, v12
	v_sub_f32_e32 v12, v14, v15
	v_add_f32_e32 v10, v12, v10
	v_add_f32_e32 v12, v17, v10
	v_mul_f32_e32 v14, v11, v12
	v_mul_f32_e32 v15, v9, v14
	v_fma_f32 v9, v14, v9, -v15
	v_fmac_f32_e32 v9, v14, v5
	v_sub_f32_e32 v5, v17, v12
	v_add_f32_e32 v5, v10, v5
	v_add_f32_e32 v10, v15, v9
	v_sub_f32_e32 v16, v12, v10
	v_sub_f32_e32 v12, v12, v16
	v_sub_f32_e32 v15, v10, v15
	v_sub_f32_e32 v10, v12, v10
	v_add_f32_e32 v5, v5, v10
	v_sub_f32_e32 v9, v15, v9
	v_add_f32_e32 v5, v9, v5
	v_add_f32_e32 v9, v13, v14
	v_add_f32_e32 v5, v16, v5
	v_sub_f32_e32 v10, v9, v13
	v_mul_f32_e32 v5, v11, v5
	v_sub_f32_e32 v10, v14, v10
	v_add_f32_e32 v5, v10, v5
	v_mul_f32_e32 v13, 0x3f317218, v4
	v_add_f32_e32 v10, v9, v5
	v_fma_f32 v14, v4, s2, -v13
	v_mul_f32_e32 v11, v10, v10
	v_mov_b32_e32 v12, 0x3ecc95a3
	v_fmac_f32_e32 v14, 0xb102e308, v4
	v_sub_f32_e32 v4, v10, v9
	v_fmamk_f32 v12, v11, 0x3e9b6dac, v12
	v_sub_f32_e32 v4, v5, v4
	v_add_f32_e32 v5, v13, v14
	v_fmaak_f32 v12, v11, v12, 0x3f2aaada
	v_sub_f32_e32 v9, v5, v13
	v_ldexp_f32 v13, v10, 1
	v_mul_f32_e32 v10, v10, v11
	v_mul_f32_e32 v10, v10, v12
	v_add_f32_e32 v11, v13, v10
	v_sub_f32_e32 v12, v11, v13
	v_ldexp_f32 v4, v4, 1
	v_sub_f32_e32 v10, v10, v12
	v_add_f32_e32 v4, v4, v10
	v_add_f32_e32 v10, v11, v4
	v_sub_f32_e32 v11, v10, v11
	v_sub_f32_e32 v4, v4, v11
	v_add_f32_e32 v11, v5, v10
	v_sub_f32_e32 v12, v11, v5
	v_sub_f32_e32 v13, v11, v12
	v_sub_f32_e32 v9, v14, v9
	v_sub_f32_e32 v5, v5, v13
	v_sub_f32_e32 v10, v10, v12
	v_add_f32_e32 v5, v10, v5
	v_add_f32_e32 v10, v9, v4
	v_sub_f32_e32 v12, v10, v9
	v_sub_f32_e32 v13, v10, v12
	v_sub_f32_e32 v9, v9, v13
	v_sub_f32_e32 v4, v4, v12
	v_add_f32_e32 v5, v10, v5
	v_add_f32_e32 v4, v4, v9
	v_add_f32_e32 v9, v11, v5
	v_sub_f32_e32 v10, v9, v11
	v_sub_f32_e32 v5, v5, v10
	v_add_f32_e32 v4, v4, v5
	s_mov_b32 s2, 0x7f800000
	v_add_f32_e32 v4, v9, v4
	v_cmp_neq_f32_e32 vcc, s2, v1
	v_mov_b32_e32 v5, 0x7f800000
	s_mov_b32 s2, 0x33800000
	v_cndmask_b32_e32 v4, v5, v4, vcc
	v_cmp_ngt_f32_e32 vcc, -1.0, v1
	v_mov_b32_e32 v5, 0x7fc00000
	v_mov_b32_e32 v9, 0
	v_cndmask_b32_e32 v4, v5, v4, vcc
	v_cmp_neq_f32_e32 vcc, -1.0, v1
	v_mov_b32_e32 v5, 0xff800000
	s_nop 0
	v_cndmask_b32_e32 v4, v5, v4, vcc
	v_cmp_lt_f32_e64 vcc, |v1|, s2
	s_mov_b64 s[2:3], src_shared_base
	v_mov_b32_e32 v5, s3
	v_cndmask_b32_e32 v1, v4, v1, vcc
	v_sub_f32_e32 v8, v8, v1
	v_lshl_add_u32 v1, v0, 2, 0
	s_nop 1
	v_add_f32_dpp v8, v8, v8 row_shr:1 row_mask:0xf bank_mask:0xf
	s_nop 1
	v_add_f32_dpp v8, v8, v8 row_shr:2 row_mask:0xf bank_mask:0xf
	s_nop 1
	v_add_f32_dpp v8, v8, v8 row_shr:4 row_mask:0xf bank_mask:0xf
	s_nop 1
	v_add_f32_dpp v8, v8, v8 row_shr:8 row_mask:0xf bank_mask:0xf
	s_nop 1
	v_add_f32_dpp v8, v8, v8 row_bcast:15 row_mask:0xa bank_mask:0xf
	s_nop 1
	v_add_f32_dpp v8, v8, v8 row_bcast:31 row_mask:0xc bank_mask:0xf
	s_nop 1
	v_readlane_b32 s2, v8, 63
	v_lshlrev_b32_e32 v2, 16, v2
	v_add_f32_e32 v2, v6, v2
	v_mov_b32_e32 v16, s2
	v_sub_f32_e32 v6, v16, v8
	v_add_f32_e32 v2, v2, v6
	v_mov_b32_e32 v6, v2
	s_nop 1
	v_max_f32_dpp v6, v6, v6 row_shr:1 row_mask:0xf bank_mask:0xf
	s_nop 1
	v_max_f32_dpp v6, v6, v6 row_shr:2 row_mask:0xf bank_mask:0xf
	s_nop 1
	v_max_f32_dpp v6, v6, v6 row_shr:4 row_mask:0xf bank_mask:0xf
	s_nop 1
	v_max_f32_dpp v6, v6, v6 row_shr:8 row_mask:0xf bank_mask:0xf
	s_nop 1
	v_max_f32_dpp v6, v6, v6 row_bcast:15 row_mask:0xa bank_mask:0xf
	s_nop 1
	v_max_f32_dpp v6, v6, v6 row_bcast:31 row_mask:0xc bank_mask:0xf
	s_nop 1
	v_readlane_b32 s2, v6, 63
	s_nop 1
	v_mov_b32_e32 v17, s2
	v_sub_f32_e32 v2, v2, v17
	v_mul_f32_e32 v2, 0x3fb8aa3b, v2
	v_exp_f32_e32 v2, v2
	s_nop 0
	ds_write_b32 v1, v2 offset:24832
